# weight-transpose gain loads de-serialized (8 tile+gain loads in flight, multiplies deferred)
# speedup vs baseline: 1.1051x; 1.0055x over previous
.LBB0_7:
	s_lshl_b32 s20, s11, 7
	s_ashr_i32 s21, s20, 31
	s_lshl_b32 s18, s10, 7
	s_lshl_b64 s[10:11], s[20:21], 2
	s_add_u32 s4, s4, s10
	v_lshlrev_b32_e32 v2, 4, v1
	s_addc_u32 s5, s5, s11
	v_and_b32_e32 v2, 0x1f0, v2
	v_mov_b32_e32 v3, 0
	v_lshl_add_u64 v[30:31], s[4:5], 0, v[2:3]
	v_ashrrev_i32_e32 v2, 5, v1
	v_add_u32_e32 v6, s18, v2
	s_movk_i32 s4, 0x1800
	v_mad_i64_i32 v[2:3], s[10:11], v6, s4, v[30:31]
	global_load_dwordx4 v[2:5], v[2:3], off nt
	s_cmp_lg_u64 s[8:9], 0
	s_cselect_b64 s[10:11], -1, 0
	s_cmp_eq_u64 s[8:9], 0
	s_cbranch_scc1 .LBB0_9
	v_ashrrev_i32_e32 v7, 31, v6
	v_lshl_add_u64 v[130:131], v[6:7], 2, s[8:9]
	global_load_dword v114, v[130:131], off
.LBB0_9:
	v_add_u32_e32 v6, 0x200, v1
	v_ashrrev_i32_e32 v6, 5, v6
	v_add_u32_e32 v10, s18, v6
	v_mad_i64_i32 v[6:7], s[4:5], v10, s4, v[30:31]
	global_load_dwordx4 v[6:9], v[6:7], off nt
	v_cndmask_b32_e64 v11, 0, 1, s[10:11]
	v_cmp_ne_u32_e64 s[4:5], 1, v11
	s_andn2_b64 vcc, exec, s[10:11]
	s_cbranch_vccnz .LBB0_11
	v_ashrrev_i32_e32 v11, 31, v10
	v_lshl_add_u64 v[130:131], v[10:11], 2, s[8:9]
	global_load_dword v116, v[130:131], off
.LBB0_11:
	v_add_u32_e32 v10, 0x400, v1
	v_ashrrev_i32_e32 v10, 5, v10
	v_add_u32_e32 v14, s18, v10
	s_movk_i32 s10, 0x1800
	v_mad_i64_i32 v[10:11], s[20:21], v14, s10, v[30:31]
	global_load_dwordx4 v[10:13], v[10:11], off nt
	s_and_b64 vcc, exec, s[4:5]
	s_cbranch_vccnz .LBB0_13
	v_ashrrev_i32_e32 v15, 31, v14
	v_lshl_add_u64 v[130:131], v[14:15], 2, s[8:9]
	global_load_dword v118, v[130:131], off
.LBB0_13:
	v_add_u32_e32 v14, 0x600, v1
	v_ashrrev_i32_e32 v14, 5, v14
	v_add_u32_e32 v18, s18, v14
	v_mad_i64_i32 v[14:15], s[10:11], v18, s10, v[30:31]
	global_load_dwordx4 v[14:17], v[14:15], off nt
	s_and_b64 vcc, exec, s[4:5]
	s_cbranch_vccnz .LBB0_15
	v_ashrrev_i32_e32 v19, 31, v18
	v_lshl_add_u64 v[130:131], v[18:19], 2, s[8:9]
	global_load_dword v120, v[130:131], off
.LBB0_15:
	v_add_u32_e32 v18, 0x800, v1
	v_ashrrev_i32_e32 v18, 5, v18
	v_add_u32_e32 v22, s18, v18
	s_movk_i32 s10, 0x1800
	v_mad_i64_i32 v[18:19], s[20:21], v22, s10, v[30:31]
	global_load_dwordx4 v[18:21], v[18:19], off nt
	s_and_b64 vcc, exec, s[4:5]
	s_cbranch_vccnz .LBB0_17
	v_ashrrev_i32_e32 v23, 31, v22
	v_lshl_add_u64 v[130:131], v[22:23], 2, s[8:9]
	global_load_dword v122, v[130:131], off
.LBB0_17:
	v_add_u32_e32 v22, 0xa00, v1
	v_ashrrev_i32_e32 v22, 5, v22
	v_add_u32_e32 v26, s18, v22
	v_mad_i64_i32 v[22:23], s[10:11], v26, s10, v[30:31]
	global_load_dwordx4 v[22:25], v[22:23], off nt
	s_and_b64 vcc, exec, s[4:5]
	s_cbranch_vccnz .LBB0_19
	v_ashrrev_i32_e32 v27, 31, v26
	v_lshl_add_u64 v[130:131], v[26:27], 2, s[8:9]
	global_load_dword v124, v[130:131], off
.LBB0_19:
	v_add_u32_e32 v26, 0xc00, v1
	v_ashrrev_i32_e32 v26, 5, v26
	v_add_u32_e32 v32, s18, v26
	s_movk_i32 s10, 0x1800
	v_mad_i64_i32 v[26:27], s[20:21], v32, s10, v[30:31]
	global_load_dwordx4 v[26:29], v[26:27], off nt
	s_and_b64 vcc, exec, s[4:5]
	s_cbranch_vccnz .LBB0_21
	v_ashrrev_i32_e32 v33, 31, v32
	v_lshl_add_u64 v[130:131], v[32:33], 2, s[8:9]
	global_load_dword v126, v[130:131], off
.LBB0_21:
	v_add_u32_e32 v32, 0xe00, v1
	v_ashrrev_i32_e32 v32, 5, v32
	v_add_u32_e32 v34, s18, v32
	v_mad_i64_i32 v[30:31], s[10:11], v34, s10, v[30:31]
	global_load_dwordx4 v[30:33], v[30:31], off nt
	s_and_b64 vcc, exec, s[4:5]
	s_cbranch_vccnz .LBB0_23
	v_ashrrev_i32_e32 v35, 31, v34
	v_lshl_add_u64 v[130:131], v[34:35], 2, s[8:9]
	global_load_dword v128, v[130:131], off
	s_waitcnt vmcnt(0)
	v_pk_mul_f32 v[4:5], v[4:5], v[114:115] op_sel_hi:[1,0]
	v_pk_mul_f32 v[2:3], v[2:3], v[114:115] op_sel_hi:[1,0]
	v_pk_mul_f32 v[8:9], v[8:9], v[116:117] op_sel_hi:[1,0]
	v_pk_mul_f32 v[6:7], v[6:7], v[116:117] op_sel_hi:[1,0]
	v_pk_mul_f32 v[12:13], v[12:13], v[118:119] op_sel_hi:[1,0]
	v_pk_mul_f32 v[10:11], v[10:11], v[118:119] op_sel_hi:[1,0]
	v_pk_mul_f32 v[16:17], v[16:17], v[120:121] op_sel_hi:[1,0]
	v_pk_mul_f32 v[14:15], v[14:15], v[120:121] op_sel_hi:[1,0]
	v_pk_mul_f32 v[20:21], v[20:21], v[122:123] op_sel_hi:[1,0]
	v_pk_mul_f32 v[18:19], v[18:19], v[122:123] op_sel_hi:[1,0]
	v_pk_mul_f32 v[24:25], v[24:25], v[124:125] op_sel_hi:[1,0]
	v_pk_mul_f32 v[22:23], v[22:23], v[124:125] op_sel_hi:[1,0]
	v_pk_mul_f32 v[28:29], v[28:29], v[126:127] op_sel_hi:[1,0]
	v_pk_mul_f32 v[26:27], v[26:27], v[126:127] op_sel_hi:[1,0]
	v_pk_mul_f32 v[32:33], v[32:33], v[128:129] op_sel_hi:[1,0]
	v_pk_mul_f32 v[30:31], v[30:31], v[128:129] op_sel_hi:[1,0]

.LBB0_35:
	s_lshl_b32 s36, s43, 7
	s_ashr_i32 s37, s36, 31
	s_lshl_b32 s42, s42, 7
	s_lshl_b64 s[36:37], s[36:37], 2
	s_add_u32 s4, s4, s36
	s_addc_u32 s5, s5, s37
	v_lshl_add_u64 v[30:31], s[4:5], 0, v[34:35]
	v_add_u32_e32 v6, s42, v40
	v_mad_i64_i32 v[2:3], s[4:5], v6, s38, v[30:31]
	global_load_dwordx4 v[2:5], v[2:3], off nt
	s_cmp_lg_u64 s[34:35], 0
	s_cselect_b64 s[36:37], -1, 0
	s_cmp_eq_u64 s[34:35], 0
	s_cbranch_scc1 .LBB0_37
	v_ashrrev_i32_e32 v7, 31, v6
	v_lshl_add_u64 v[130:131], v[6:7], 2, s[34:35]
	global_load_dword v114, v[130:131], off
.LBB0_37:
	v_add_u32_e32 v10, s42, v41
	v_mad_i64_i32 v[6:7], s[4:5], v10, s38, v[30:31]
	global_load_dwordx4 v[6:9], v[6:7], off nt
	v_cndmask_b32_e64 v11, 0, 1, s[36:37]
	v_cmp_ne_u32_e64 s[4:5], 1, v11
	s_andn2_b64 vcc, exec, s[36:37]
	s_cbranch_vccnz .LBB0_39
	v_ashrrev_i32_e32 v11, 31, v10
	v_lshl_add_u64 v[130:131], v[10:11], 2, s[34:35]
	global_load_dword v116, v[130:131], off
.LBB0_39:
	v_add_u32_e32 v14, s42, v42
	v_mad_i64_i32 v[10:11], s[36:37], v14, s38, v[30:31]
	global_load_dwordx4 v[10:13], v[10:11], off nt
	s_and_b64 vcc, exec, s[4:5]
	s_cbranch_vccnz .LBB0_41
	v_ashrrev_i32_e32 v15, 31, v14
	v_lshl_add_u64 v[130:131], v[14:15], 2, s[34:35]
	global_load_dword v118, v[130:131], off
.LBB0_41:
	v_add_u32_e32 v18, s42, v43
	v_mad_i64_i32 v[14:15], s[36:37], v18, s38, v[30:31]
	global_load_dwordx4 v[14:17], v[14:15], off nt
	s_and_b64 vcc, exec, s[4:5]
	s_cbranch_vccnz .LBB0_43
	v_ashrrev_i32_e32 v19, 31, v18
	v_lshl_add_u64 v[130:131], v[18:19], 2, s[34:35]
	global_load_dword v120, v[130:131], off
.LBB0_43:
	v_add_u32_e32 v22, s42, v44
	v_mad_i64_i32 v[18:19], s[36:37], v22, s38, v[30:31]
	global_load_dwordx4 v[18:21], v[18:19], off nt
	s_and_b64 vcc, exec, s[4:5]
	s_cbranch_vccnz .LBB0_45
	v_ashrrev_i32_e32 v23, 31, v22
	v_lshl_add_u64 v[130:131], v[22:23], 2, s[34:35]
	global_load_dword v122, v[130:131], off
.LBB0_45:
	v_add_u32_e32 v26, s42, v45
	v_mad_i64_i32 v[22:23], s[36:37], v26, s38, v[30:31]
	global_load_dwordx4 v[22:25], v[22:23], off nt
	s_and_b64 vcc, exec, s[4:5]
	s_cbranch_vccnz .LBB0_47
	v_ashrrev_i32_e32 v27, 31, v26
	v_lshl_add_u64 v[130:131], v[26:27], 2, s[34:35]
	global_load_dword v124, v[130:131], off
.LBB0_47:
	v_add_u32_e32 v32, s42, v46
	v_mad_i64_i32 v[26:27], s[36:37], v32, s38, v[30:31]
	global_load_dwordx4 v[26:29], v[26:27], off nt
	s_and_b64 vcc, exec, s[4:5]
	s_cbranch_vccnz .LBB0_49
	v_ashrrev_i32_e32 v33, 31, v32
	v_lshl_add_u64 v[130:131], v[32:33], 2, s[34:35]
	global_load_dword v126, v[130:131], off
.LBB0_49:
	v_add_u32_e32 v38, s42, v47
	v_mad_i64_i32 v[30:31], s[36:37], v38, s38, v[30:31]
	global_load_dwordx4 v[30:33], v[30:31], off nt
	s_and_b64 vcc, exec, s[4:5]
	s_cbranch_vccnz .LBB0_25
	v_ashrrev_i32_e32 v39, 31, v38
	v_lshl_add_u64 v[130:131], v[38:39], 2, s[34:35]
	global_load_dword v128, v[130:131], off
	s_waitcnt vmcnt(0)
	v_pk_mul_f32 v[4:5], v[4:5], v[114:115] op_sel_hi:[1,0]
	v_pk_mul_f32 v[2:3], v[2:3], v[114:115] op_sel_hi:[1,0]
	v_pk_mul_f32 v[8:9], v[8:9], v[116:117] op_sel_hi:[1,0]
	v_pk_mul_f32 v[6:7], v[6:7], v[116:117] op_sel_hi:[1,0]
	v_pk_mul_f32 v[12:13], v[12:13], v[118:119] op_sel_hi:[1,0]
	v_pk_mul_f32 v[10:11], v[10:11], v[118:119] op_sel_hi:[1,0]
	v_pk_mul_f32 v[16:17], v[16:17], v[120:121] op_sel_hi:[1,0]
	v_pk_mul_f32 v[14:15], v[14:15], v[120:121] op_sel_hi:[1,0]
	v_pk_mul_f32 v[20:21], v[20:21], v[122:123] op_sel_hi:[1,0]
	v_pk_mul_f32 v[18:19], v[18:19], v[122:123] op_sel_hi:[1,0]
	v_pk_mul_f32 v[24:25], v[24:25], v[124:125] op_sel_hi:[1,0]
	v_pk_mul_f32 v[22:23], v[22:23], v[124:125] op_sel_hi:[1,0]
	v_pk_mul_f32 v[28:29], v[28:29], v[126:127] op_sel_hi:[1,0]
	v_pk_mul_f32 v[26:27], v[26:27], v[126:127] op_sel_hi:[1,0]
	v_pk_mul_f32 v[32:33], v[32:33], v[128:129] op_sel_hi:[1,0]
	v_pk_mul_f32 v[30:31], v[30:31], v[128:129] op_sel_hi:[1,0]
	s_branch .LBB0_25

.LBB0_399:
	s_ashr_i32 s17, s16, 31
	v_lshlrev_b32_e32 v0, 4, v34
	s_lshl_b64 s[16:17], s[16:17], 2
	v_and_b32_e32 v174, 0x1f0, v0
	v_ashrrev_i32_e32 v0, 5, v34
	s_add_u32 s12, s12, s16
	v_add_u32_e32 v4, s54, v0
	s_addc_u32 s13, s13, s17
	v_ashrrev_i32_e32 v5, 31, v4
	v_lshl_add_u64 v[28:29], s[12:13], 0, v[174:175]
	v_mul_lo_u32 v2, s10, v5
	v_mul_lo_u32 v3, s11, v4
	v_mad_u64_u32 v[0:1], s[12:13], s10, v4, 0
	v_add3_u32 v1, v1, v2, v3
	v_lshl_add_u64 v[0:1], v[0:1], 2, v[28:29]
	global_load_dwordx4 v[0:3], v[0:1], off nt
	s_cmp_lg_u64 s[50:51], 0
	s_cselect_b64 s[12:13], -1, 0
	s_cmp_eq_u64 s[50:51], 0
	s_cbranch_scc1 .LBB0_401
	v_lshl_add_u64 v[130:131], v[4:5], 2, s[50:51]
	global_load_dword v114, v[130:131], off
.LBB0_401:
	v_add_u32_e32 v4, 0x200, v34
	v_ashrrev_i32_e32 v4, 5, v4
	v_add_u32_e32 v8, s54, v4
	v_ashrrev_i32_e32 v9, 31, v8
	v_mul_lo_u32 v6, s10, v9
	v_mul_lo_u32 v7, s11, v8
	v_mad_u64_u32 v[4:5], s[16:17], s10, v8, 0
	v_add3_u32 v5, v5, v6, v7
	v_lshl_add_u64 v[4:5], v[4:5], 2, v[28:29]
	global_load_dwordx4 v[4:7], v[4:5], off nt
	v_cndmask_b32_e64 v10, 0, 1, s[12:13]
	v_cmp_ne_u32_e64 s[22:23], 1, v10
	s_andn2_b64 vcc, exec, s[12:13]
	s_cbranch_vccnz .LBB0_403
	v_lshl_add_u64 v[130:131], v[8:9], 2, s[50:51]
	global_load_dword v116, v[130:131], off
.LBB0_403:
	v_add_u32_e32 v8, 0x400, v34
	v_ashrrev_i32_e32 v8, 5, v8
	v_add_u32_e32 v12, s54, v8
	v_ashrrev_i32_e32 v13, 31, v12
	v_mul_lo_u32 v10, s10, v13
	v_mul_lo_u32 v11, s11, v12
	v_mad_u64_u32 v[8:9], s[12:13], s10, v12, 0
	v_add3_u32 v9, v9, v10, v11
	v_lshl_add_u64 v[8:9], v[8:9], 2, v[28:29]
	global_load_dwordx4 v[8:11], v[8:9], off nt
	s_and_b64 vcc, exec, s[22:23]
	s_cbranch_vccnz .LBB0_405
	v_lshl_add_u64 v[130:131], v[12:13], 2, s[50:51]
	global_load_dword v118, v[130:131], off
.LBB0_405:
	v_add_u32_e32 v12, 0x600, v34
	v_ashrrev_i32_e32 v12, 5, v12
	v_add_u32_e32 v16, s54, v12
	v_ashrrev_i32_e32 v17, 31, v16
	v_mul_lo_u32 v14, s10, v17
	v_mul_lo_u32 v15, s11, v16
	v_mad_u64_u32 v[12:13], s[12:13], s10, v16, 0
	v_add3_u32 v13, v13, v14, v15
	v_lshl_add_u64 v[12:13], v[12:13], 2, v[28:29]
	global_load_dwordx4 v[12:15], v[12:13], off nt
	s_and_b64 vcc, exec, s[22:23]
	s_cbranch_vccnz .LBB0_407
	v_lshl_add_u64 v[130:131], v[16:17], 2, s[50:51]
	global_load_dword v120, v[130:131], off
.LBB0_407:
	v_add_u32_e32 v16, 0x800, v34
	v_ashrrev_i32_e32 v16, 5, v16
	v_add_u32_e32 v20, s54, v16
	v_ashrrev_i32_e32 v21, 31, v20
	v_mul_lo_u32 v18, s10, v21
	v_mul_lo_u32 v19, s11, v20
	v_mad_u64_u32 v[16:17], s[12:13], s10, v20, 0
	v_add3_u32 v17, v17, v18, v19
	v_lshl_add_u64 v[16:17], v[16:17], 2, v[28:29]
	global_load_dwordx4 v[16:19], v[16:17], off nt
	s_and_b64 vcc, exec, s[22:23]
	s_cbranch_vccnz .LBB0_409
	v_lshl_add_u64 v[130:131], v[20:21], 2, s[50:51]
	global_load_dword v122, v[130:131], off
.LBB0_409:
	v_add_u32_e32 v20, 0xa00, v34
	v_ashrrev_i32_e32 v20, 5, v20
	v_add_u32_e32 v24, s54, v20
	v_ashrrev_i32_e32 v25, 31, v24
	v_mul_lo_u32 v22, s10, v25
	v_mul_lo_u32 v23, s11, v24
	v_mad_u64_u32 v[20:21], s[12:13], s10, v24, 0
	v_add3_u32 v21, v21, v22, v23
	v_lshl_add_u64 v[20:21], v[20:21], 2, v[28:29]
	global_load_dwordx4 v[20:23], v[20:21], off nt
	s_and_b64 vcc, exec, s[22:23]
	s_cbranch_vccnz .LBB0_411
	v_lshl_add_u64 v[130:131], v[24:25], 2, s[50:51]
	global_load_dword v124, v[130:131], off
.LBB0_411:
	v_add_u32_e32 v24, 0xc00, v34
	v_ashrrev_i32_e32 v24, 5, v24
	v_add_u32_e32 v30, s54, v24
	v_ashrrev_i32_e32 v31, 31, v30
	v_mul_lo_u32 v26, s10, v31
	v_mul_lo_u32 v27, s11, v30
	v_mad_u64_u32 v[24:25], s[12:13], s10, v30, 0
	v_add3_u32 v25, v25, v26, v27
	v_lshl_add_u64 v[24:25], v[24:25], 2, v[28:29]
	global_load_dwordx4 v[24:27], v[24:25], off nt
	s_and_b64 vcc, exec, s[22:23]
	s_cbranch_vccnz .LBB0_413
	v_lshl_add_u64 v[130:131], v[30:31], 2, s[50:51]
	global_load_dword v126, v[130:131], off
.LBB0_413:
	v_add_u32_e32 v30, 0xe00, v34
	v_ashrrev_i32_e32 v30, 5, v30
	v_add_u32_e32 v32, s54, v30
	v_ashrrev_i32_e32 v33, 31, v32
	v_mul_lo_u32 v35, s10, v33
	v_mul_lo_u32 v36, s11, v32
	v_mad_u64_u32 v[30:31], s[10:11], s10, v32, 0
	v_add3_u32 v31, v31, v35, v36
	v_lshl_add_u64 v[28:29], v[30:31], 2, v[28:29]
	global_load_dwordx4 v[28:31], v[28:29], off nt
	s_and_b64 vcc, exec, s[22:23]
	s_cbranch_vccnz .LBB0_415
	v_lshl_add_u64 v[130:131], v[32:33], 2, s[50:51]
	global_load_dword v128, v[130:131], off
	s_waitcnt vmcnt(0)
	v_pk_mul_f32 v[2:3], v[2:3], v[114:115] op_sel_hi:[1,0]
	v_pk_mul_f32 v[0:1], v[0:1], v[114:115] op_sel_hi:[1,0]
	v_pk_mul_f32 v[6:7], v[6:7], v[116:117] op_sel_hi:[1,0]
	v_pk_mul_f32 v[4:5], v[4:5], v[116:117] op_sel_hi:[1,0]
	v_pk_mul_f32 v[10:11], v[10:11], v[118:119] op_sel_hi:[1,0]
	v_pk_mul_f32 v[8:9], v[8:9], v[118:119] op_sel_hi:[1,0]
	v_pk_mul_f32 v[14:15], v[14:15], v[120:121] op_sel_hi:[1,0]
	v_pk_mul_f32 v[12:13], v[12:13], v[120:121] op_sel_hi:[1,0]
	v_pk_mul_f32 v[18:19], v[18:19], v[122:123] op_sel_hi:[1,0]
	v_pk_mul_f32 v[16:17], v[16:17], v[122:123] op_sel_hi:[1,0]
	v_pk_mul_f32 v[22:23], v[22:23], v[124:125] op_sel_hi:[1,0]
	v_pk_mul_f32 v[20:21], v[20:21], v[124:125] op_sel_hi:[1,0]
	v_pk_mul_f32 v[26:27], v[26:27], v[126:127] op_sel_hi:[1,0]
	v_pk_mul_f32 v[24:25], v[24:25], v[126:127] op_sel_hi:[1,0]
	v_pk_mul_f32 v[30:31], v[30:31], v[128:129] op_sel_hi:[1,0]
	v_pk_mul_f32 v[28:29], v[28:29], v[128:129] op_sel_hi:[1,0]

.LBB0_451:
	s_ashr_i32 s13, s12, 31
	s_lshl_b64 s[12:13], s[12:13], 2
	s_add_u32 s12, s22, s12
	v_add_u32_e32 v4, s85, v36
	s_addc_u32 s13, s23, s13
	v_ashrrev_i32_e32 v5, 31, v4
	v_lshl_add_u64 v[28:29], s[12:13], 0, v[174:175]
	v_mul_lo_u32 v2, s10, v5
	v_mul_lo_u32 v3, s11, v4
	v_mad_u64_u32 v[0:1], s[12:13], s10, v4, 0
	v_add3_u32 v1, v1, v2, v3
	v_lshl_add_u64 v[0:1], v[0:1], 2, v[28:29]
	global_load_dwordx4 v[0:3], v[0:1], off nt
	s_cmp_lg_u64 s[58:59], 0
	s_cselect_b64 s[12:13], -1, 0
	s_cmp_eq_u64 s[58:59], 0
	s_cbranch_scc1 .LBB0_453
	v_lshl_add_u64 v[130:131], v[4:5], 2, s[58:59]
	global_load_dword v114, v[130:131], off
.LBB0_453:
	v_add_u32_e32 v8, s85, v37
	v_ashrrev_i32_e32 v9, 31, v8
	v_mul_lo_u32 v6, s10, v9
	v_mul_lo_u32 v7, s11, v8
	v_mad_u64_u32 v[4:5], s[16:17], s10, v8, 0
	v_add3_u32 v5, v5, v6, v7
	v_lshl_add_u64 v[4:5], v[4:5], 2, v[28:29]
	global_load_dwordx4 v[4:7], v[4:5], off nt
	v_cndmask_b32_e64 v10, 0, 1, s[12:13]
	v_cmp_ne_u32_e64 s[22:23], 1, v10
	s_andn2_b64 vcc, exec, s[12:13]
	s_cbranch_vccnz .LBB0_455
	v_lshl_add_u64 v[130:131], v[8:9], 2, s[58:59]
	global_load_dword v116, v[130:131], off
.LBB0_455:
	v_add_u32_e32 v12, s85, v38
	v_ashrrev_i32_e32 v13, 31, v12
	v_mul_lo_u32 v10, s10, v13
	v_mul_lo_u32 v11, s11, v12
	v_mad_u64_u32 v[8:9], s[12:13], s10, v12, 0
	v_add3_u32 v9, v9, v10, v11
	v_lshl_add_u64 v[8:9], v[8:9], 2, v[28:29]
	global_load_dwordx4 v[8:11], v[8:9], off nt
	s_and_b64 vcc, exec, s[22:23]
	s_cbranch_vccnz .LBB0_457
	v_lshl_add_u64 v[130:131], v[12:13], 2, s[58:59]
	global_load_dword v118, v[130:131], off
.LBB0_457:
	v_add_u32_e32 v16, s85, v39
	v_ashrrev_i32_e32 v17, 31, v16
	v_mul_lo_u32 v14, s10, v17
	v_mul_lo_u32 v15, s11, v16
	v_mad_u64_u32 v[12:13], s[12:13], s10, v16, 0
	v_add3_u32 v13, v13, v14, v15
	v_lshl_add_u64 v[12:13], v[12:13], 2, v[28:29]
	global_load_dwordx4 v[12:15], v[12:13], off nt
	s_and_b64 vcc, exec, s[22:23]
	s_cbranch_vccnz .LBB0_459
	v_lshl_add_u64 v[130:131], v[16:17], 2, s[58:59]
	global_load_dword v120, v[130:131], off
.LBB0_459:
	v_add_u32_e32 v20, s85, v40
	v_ashrrev_i32_e32 v21, 31, v20
	v_mul_lo_u32 v18, s10, v21
	v_mul_lo_u32 v19, s11, v20
	v_mad_u64_u32 v[16:17], s[12:13], s10, v20, 0
	v_add3_u32 v17, v17, v18, v19
	v_lshl_add_u64 v[16:17], v[16:17], 2, v[28:29]
	global_load_dwordx4 v[16:19], v[16:17], off nt
	s_and_b64 vcc, exec, s[22:23]
	s_cbranch_vccnz .LBB0_461
	v_lshl_add_u64 v[130:131], v[20:21], 2, s[58:59]
	global_load_dword v122, v[130:131], off
.LBB0_461:
	v_add_u32_e32 v24, s85, v41
	v_ashrrev_i32_e32 v25, 31, v24
	v_mul_lo_u32 v22, s10, v25
	v_mul_lo_u32 v23, s11, v24
	v_mad_u64_u32 v[20:21], s[12:13], s10, v24, 0
	v_add3_u32 v21, v21, v22, v23
	v_lshl_add_u64 v[20:21], v[20:21], 2, v[28:29]
	global_load_dwordx4 v[20:23], v[20:21], off nt
	s_and_b64 vcc, exec, s[22:23]
	s_cbranch_vccnz .LBB0_463
	v_lshl_add_u64 v[130:131], v[24:25], 2, s[58:59]
	global_load_dword v124, v[130:131], off
.LBB0_463:
	v_add_u32_e32 v30, s85, v42
	v_ashrrev_i32_e32 v31, 31, v30
	v_mul_lo_u32 v26, s10, v31
	v_mul_lo_u32 v27, s11, v30
	v_mad_u64_u32 v[24:25], s[12:13], s10, v30, 0
	v_add3_u32 v25, v25, v26, v27
	v_lshl_add_u64 v[24:25], v[24:25], 2, v[28:29]
	global_load_dwordx4 v[24:27], v[24:25], off nt
	s_and_b64 vcc, exec, s[22:23]
	s_cbranch_vccnz .LBB0_465
	v_lshl_add_u64 v[130:131], v[30:31], 2, s[58:59]
	global_load_dword v126, v[130:131], off
.LBB0_465:
	v_add_u32_e32 v34, s85, v43
	v_ashrrev_i32_e32 v35, 31, v34
	v_mul_lo_u32 v33, s10, v35
	v_mul_lo_u32 v60, s11, v34
	v_mad_u64_u32 v[30:31], s[10:11], s10, v34, 0
	v_add3_u32 v31, v31, v33, v60
	v_lshl_add_u64 v[28:29], v[30:31], 2, v[28:29]
	global_load_dwordx4 v[28:31], v[28:29], off nt
	s_and_b64 vcc, exec, s[22:23]
	s_cbranch_vccnz .LBB0_417
	v_lshl_add_u64 v[130:131], v[34:35], 2, s[58:59]
	global_load_dword v128, v[130:131], off
	s_waitcnt vmcnt(0)
	v_pk_mul_f32 v[2:3], v[2:3], v[114:115] op_sel_hi:[1,0]
	v_pk_mul_f32 v[0:1], v[0:1], v[114:115] op_sel_hi:[1,0]
	v_pk_mul_f32 v[6:7], v[6:7], v[116:117] op_sel_hi:[1,0]
	v_pk_mul_f32 v[4:5], v[4:5], v[116:117] op_sel_hi:[1,0]
	v_pk_mul_f32 v[10:11], v[10:11], v[118:119] op_sel_hi:[1,0]
	v_pk_mul_f32 v[8:9], v[8:9], v[118:119] op_sel_hi:[1,0]
	v_pk_mul_f32 v[14:15], v[14:15], v[120:121] op_sel_hi:[1,0]
	v_pk_mul_f32 v[12:13], v[12:13], v[120:121] op_sel_hi:[1,0]
	v_pk_mul_f32 v[18:19], v[18:19], v[122:123] op_sel_hi:[1,0]
	v_pk_mul_f32 v[16:17], v[16:17], v[122:123] op_sel_hi:[1,0]
	v_pk_mul_f32 v[22:23], v[22:23], v[124:125] op_sel_hi:[1,0]
	v_pk_mul_f32 v[20:21], v[20:21], v[124:125] op_sel_hi:[1,0]
	v_pk_mul_f32 v[26:27], v[26:27], v[126:127] op_sel_hi:[1,0]
	v_pk_mul_f32 v[24:25], v[24:25], v[126:127] op_sel_hi:[1,0]
	v_pk_mul_f32 v[30:31], v[30:31], v[128:129] op_sel_hi:[1,0]
	v_pk_mul_f32 v[28:29], v[28:29], v[128:129] op_sel_hi:[1,0]
	s_branch .LBB0_417
